# v35 = v34 without the redundant second workgroup barrier after P6's memory-attention unit
# baseline (speedup 1.0000x reference)
.LBB0_979:
	s_cmp_lg_u32 0, -1
	s_cselect_b32 s8, 0, 0
	s_add_i32 s8, s8, 0xc000
	v_add_u32_e32 v32, s8, v132
	v_add3_u32 v33, v32, v137, v138
	v_add_f32_e32 v32, v80, v81
	v_add_f32_e32 v32, v82, v32
	v_add_f32_e32 v32, v83, v32
	v_add_f32_e32 v32, v84, v32
	v_add_f32_e32 v32, v85, v32
	v_add_f32_e32 v32, v86, v32
	v_add_f32_e32 v32, v87, v32
	v_add_f32_e32 v32, v88, v32
	v_add_f32_e32 v32, v89, v32
	v_add_f32_e32 v32, v90, v32
	v_add_f32_e32 v32, v91, v32
	v_add_f32_e32 v32, v92, v32
	v_add_f32_e32 v32, v93, v32
	v_add_f32_e32 v32, v94, v32
	v_add_f32_e32 v32, v95, v32
	v_add_f32_e32 v32, v32, v48
	v_add_f32_e32 v32, v49, v32
	v_add_f32_e32 v32, v50, v32
	v_add_f32_e32 v32, v51, v32
	v_add_f32_e32 v32, v52, v32
	v_add_f32_e32 v32, v53, v32
	v_add_f32_e32 v32, v54, v32
	v_add_f32_e32 v32, v55, v32
	v_add_f32_e32 v32, v56, v32
	v_add_f32_e32 v32, v57, v32
	v_add_f32_e32 v32, v58, v32
	v_add_f32_e32 v32, v59, v32
	v_add_f32_e32 v32, v60, v32
	v_add_f32_e32 v32, v61, v32
	v_add_f32_e32 v32, v62, v32
	v_add_f32_e32 v32, v63, v32
	v_add_f32_e32 v32, v40, v32
	v_cvt_pk_bf16_f32 v34, v80, v81
	v_cvt_pk_bf16_f32 v35, v82, v83
	v_cvt_pk_bf16_f32 v36, v84, v85
	v_cvt_pk_bf16_f32 v37, v86, v87
	v_cvt_pk_bf16_f32 v38, v88, v89
	v_cvt_pk_bf16_f32 v39, v90, v91
	v_cvt_pk_bf16_f32 v40, v92, v93
	v_cvt_pk_bf16_f32 v41, v94, v95
	v_cvt_pk_bf16_f32 v42, v48, v49
	v_cvt_pk_bf16_f32 v43, v50, v51
	v_cvt_pk_bf16_f32 v44, v52, v53
	v_cvt_pk_bf16_f32 v45, v54, v55
	v_cvt_pk_bf16_f32 v46, v56, v57
	v_cvt_pk_bf16_f32 v47, v58, v59
	v_cvt_pk_bf16_f32 v48, v60, v61
	v_cvt_pk_bf16_f32 v49, v62, v63
	ds_read_b64_tr_b16 v[50:51],v33 offset:0
	ds_read_b64_tr_b16 v[52:53],v33 offset:512
	ds_read_b64_tr_b16 v[54:55],v33 offset:1024
	ds_read_b64_tr_b16 v[56:57],v33 offset:1536
	ds_read_b64_tr_b16 v[58:59],v33 offset:2048
	ds_read_b64_tr_b16 v[60:61],v33 offset:2560
	ds_read_b64_tr_b16 v[62:63],v33 offset:3072
	ds_read_b64_tr_b16 v[64:65],v33 offset:3584
	s_waitcnt lgkmcnt(0)
	s_nop 0
	v_mfma_f32_32x32x16_bf16 v[0:15], v[34:37], v[50:53], v[0:15]
	ds_read_b64_tr_b16 v[50:51],v33 offset:4096
	ds_read_b64_tr_b16 v[52:53],v33 offset:4608
	v_mfma_f32_32x32x16_bf16 v[0:15], v[38:41], v[54:57], v[0:15]
	ds_read_b64_tr_b16 v[54:55],v33 offset:5120
	ds_read_b64_tr_b16 v[56:57],v33 offset:5632
	v_mfma_f32_32x32x16_bf16 v[0:15], v[42:45], v[58:61], v[0:15]
	ds_read_b64_tr_b16 v[58:59],v33 offset:6144
	ds_read_b64_tr_b16 v[60:61],v33 offset:6656
	ds_read_b64_tr_b16 v[66:67],v33 offset:7168
	ds_read_b64_tr_b16 v[68:69],v33 offset:7680
	s_waitcnt lgkmcnt(0)
	v_mfma_f32_32x32x16_bf16 v[0:15], v[46:49], v[62:65], v[0:15]
	v_mfma_f32_32x32x16_bf16 v[16:31], v[34:37], v[50:53], v[16:31]
	v_mov_b32_e32 v33, v32
	s_nop 1
	v_permlane32_swap_b32_e32 v32, v33
	v_mfma_f32_32x32x16_bf16 v[16:31], v[38:41], v[54:57], v[16:31]
	v_mfma_f32_32x32x16_bf16 v[16:31], v[42:45], v[58:61], v[16:31]
	v_mfma_f32_32x32x16_bf16 v[16:31], v[46:49], v[66:69], v[16:31]
	s_and_saveexec_b64 s[8:9], s[0:1]
	v_add_f32_e32 v32, v32, v33
	v_lshl_add_u32 v33, v184, 2, s15
	ds_write_b32 v33, v32 offset:128
	s_or_b64 exec, exec, s[8:9]
	s_add_u32 s38, s4, 0x3800000
	s_addc_u32 s39, s5, 0
	s_add_u32 s28, s4, 0x700000
	s_addc_u32 s29, s5, 0
	s_waitcnt lgkmcnt(0)
	s_add_u32 s30, s4, 0xf9ff000
	ds_read_b128 v[32:35], v140 offset:128
	ds_read_b128 v[36:39], v140 offset:160
	s_addc_u32 s31, s5, 0
	s_add_u32 s20, s4, 0xf800000
	s_addc_u32 s21, s5, 0
	s_lshl_b64 s[0:1], s[6:7], 24
	s_add_u32 s0, s4, s0
	s_addc_u32 s1, s5, s1
	s_waitcnt lgkmcnt(1)
	v_rcp_f32_e32 v40, v32
	s_add_u32 s4, s0, s14
	s_addc_u32 s1, s1, 0
	s_lshl_b32 s0, s90, 12
	s_add_i32 s0, s0, 0
	v_rcp_f32_e32 v41, v33
	s_add_i32 s0, s0, 0x12800
	v_lshlrev_b32_e32 v48, 9, v136
	v_lshlrev_b32_e32 v49, 1, v135
	v_mul_f32_e32 v0, v0, v40
	v_add3_u32 v48, s0, v48, v49
	v_cvt_pk_bf16_f32 v0, v0, s0
	ds_write_b16 v48, v0
	v_mul_f32_e32 v0, v16, v40
	v_cvt_pk_bf16_f32 v0, v0, s0
	v_rcp_f32_e32 v42, v34
	ds_write_b16 v48, v0 offset:64
	v_mul_f32_e32 v0, v1, v41
	v_cvt_pk_bf16_f32 v0, v0, s0
	ds_write_b16 v48, v0 offset:128
	v_mul_f32_e32 v0, v17, v41
	v_cvt_pk_bf16_f32 v0, v0, s0
	v_rcp_f32_e32 v43, v35
	ds_write_b16 v48, v0 offset:192
	v_mul_f32_e32 v0, v2, v42
	v_cvt_pk_bf16_f32 v0, v0, s0
	ds_write_b16 v48, v0 offset:256
	v_mul_f32_e32 v0, v18, v42
	v_cvt_pk_bf16_f32 v0, v0, s0
	s_waitcnt lgkmcnt(5)
	v_rcp_f32_e32 v44, v36
	ds_write_b16 v48, v0 offset:320
	v_mul_f32_e32 v0, v3, v43
	v_cvt_pk_bf16_f32 v0, v0, s0
	ds_write_b16 v48, v0 offset:384
	v_mul_f32_e32 v0, v19, v43
	v_cvt_pk_bf16_f32 v0, v0, s0
	v_rcp_f32_e32 v45, v37
	ds_write_b16 v48, v0 offset:448
	v_mul_f32_e32 v0, v4, v44
	v_cvt_pk_bf16_f32 v0, v0, s0
	ds_write_b16 v48, v0 offset:1024
	v_mul_f32_e32 v0, v20, v44
	v_cvt_pk_bf16_f32 v0, v0, s0
	v_rcp_f32_e32 v46, v38
	ds_write_b16 v48, v0 offset:1088
	v_mul_f32_e32 v0, v5, v45
	v_cvt_pk_bf16_f32 v0, v0, s0
	ds_write_b16 v48, v0 offset:1152
	v_mul_f32_e32 v0, v21, v45
	ds_read_b128 v[32:35], v140 offset:192
	v_cvt_pk_bf16_f32 v0, v0, s0
	v_rcp_f32_e32 v47, v39
	ds_write_b16 v48, v0 offset:1216
	v_mul_f32_e32 v0, v6, v46
	v_cvt_pk_bf16_f32 v0, v0, s0
	ds_write_b16 v48, v0 offset:1280
	v_mul_f32_e32 v0, v22, v46
	v_cvt_pk_bf16_f32 v0, v0, s0
	ds_read_b128 v[36:39], v140 offset:224
	s_waitcnt lgkmcnt(3)
	v_rcp_f32_e32 v32, v32
	ds_write_b16 v48, v0 offset:1344
	v_mul_f32_e32 v0, v7, v47
	v_cvt_pk_bf16_f32 v0, v0, s0
	ds_write_b16 v48, v0 offset:1408
	v_mul_f32_e32 v0, v23, v47
	v_cvt_pk_bf16_f32 v0, v0, s0
	v_rcp_f32_e32 v33, v33
	ds_write_b16 v48, v0 offset:1472
	v_mul_f32_e32 v0, v8, v32
	v_cvt_pk_bf16_f32 v0, v0, s0
	ds_write_b16 v48, v0 offset:2048
	v_mul_f32_e32 v0, v24, v32
	v_cvt_pk_bf16_f32 v0, v0, s0
	v_rcp_f32_e32 v34, v34
	ds_write_b16 v48, v0 offset:2112
	v_mul_f32_e32 v0, v9, v33
	v_cvt_pk_bf16_f32 v0, v0, s0
	ds_write_b16 v48, v0 offset:2176
	v_mul_f32_e32 v0, v25, v33
	v_cvt_pk_bf16_f32 v0, v0, s0
	v_rcp_f32_e32 v35, v35
	ds_write_b16 v48, v0 offset:2240
	v_mul_f32_e32 v0, v10, v34
	v_cvt_pk_bf16_f32 v0, v0, s0
	ds_write_b16 v48, v0 offset:2304
	v_mul_f32_e32 v0, v26, v34
	v_cvt_pk_bf16_f32 v0, v0, s0
	s_waitcnt lgkmcnt(8)
	v_rcp_f32_e32 v36, v36
	ds_write_b16 v48, v0 offset:2368
	v_mul_f32_e32 v0, v11, v35
	v_cvt_pk_bf16_f32 v0, v0, s0
	ds_write_b16 v48, v0 offset:2432
	v_mul_f32_e32 v0, v27, v35
	v_cvt_pk_bf16_f32 v0, v0, s0
	v_rcp_f32_e32 v37, v37
	ds_write_b16 v48, v0 offset:2496
	v_mul_f32_e32 v0, v12, v36
	v_cvt_pk_bf16_f32 v0, v0, s0
	ds_write_b16 v48, v0 offset:3072
	v_mul_f32_e32 v0, v28, v36
	v_cvt_pk_bf16_f32 v0, v0, s0
	v_rcp_f32_e32 v38, v38
	ds_write_b16 v48, v0 offset:3136
	v_mul_f32_e32 v0, v13, v37
	v_cvt_pk_bf16_f32 v0, v0, s0
	ds_write_b16 v48, v0 offset:3200
	v_mul_f32_e32 v0, v29, v37
	v_cvt_pk_bf16_f32 v0, v0, s0
	v_rcp_f32_e32 v39, v39
	ds_write_b16 v48, v0 offset:3264
	v_mul_f32_e32 v0, v14, v38
	v_cvt_pk_bf16_f32 v0, v0, s0
	ds_write_b16 v48, v0 offset:3328
	v_mul_f32_e32 v0, v30, v38
	v_cvt_pk_bf16_f32 v0, v0, s0
	ds_write_b16 v48, v0 offset:3392
	v_mul_f32_e32 v0, v15, v39
	v_cvt_pk_bf16_f32 v0, v0, s0
	ds_write_b16 v48, v0 offset:3456
	v_mul_f32_e32 v0, v31, v39
	v_cvt_pk_bf16_f32 v0, v0, s0
	s_lshl_b64 s[2:3], s[2:3], 11
	ds_write_b16 v48, v0 offset:3520
	s_add_u32 s2, s4, s2
	v_and_b32_e32 v0, 56, v134
	s_addc_u32 s3, s1, s3
	v_ashrrev_i32_e32 v116, 3, v184
	v_lshlrev_b32_e32 v124, 1, v0
	v_mov_b32_e32 v125, 0
	v_lshl_add_u64 v[16:17], s[2:3], 0, v[124:125]
	s_mov_b64 s[2:3], 0xb000600
	v_ashrrev_i32_e32 v117, 31, v116
	v_lshl_add_u64 v[18:19], v[16:17], 0, s[2:3]
	v_lshlrev_b64 v[20:21], 11, v[116:117]
	s_waitcnt lgkmcnt(0)
	v_lshl_add_u64 v[0:1], v[18:19], 0, v[20:21]
	global_load_dwordx4 v[0:3], v[0:1], off
	v_add_u32_e32 v22, 8, v116
	v_ashrrev_i32_e32 v23, 31, v22
	v_lshlrev_b64 v[24:25], 11, v[22:23]
	v_lshl_add_u64 v[4:5], v[18:19], 0, v[24:25]
	global_load_dwordx4 v[4:7], v[4:5], off
	v_add_u32_e32 v26, 16, v116
	v_ashrrev_i32_e32 v27, 31, v26
	v_lshlrev_b64 v[28:29], 11, v[26:27]
	v_lshl_add_u64 v[8:9], v[18:19], 0, v[28:29]
	v_add_u32_e32 v27, s0, v124
	global_load_dwordx4 v[8:11], v[8:9], off
	v_lshl_add_u32 v12, v116, 7, v27
	ds_read_b128 v[12:15], v12
	s_mov_b64 s[0:1], 0xd800600
	v_lshl_add_u64 v[30:31], v[16:17], 0, s[0:1]
	v_lshl_add_u64 v[20:21], v[30:31], 0, v[20:21]
	s_add_i32 s33, s70, 0
	s_waitcnt lgkmcnt(0)
	v_lshlrev_b32_e32 v16, 16, v12
	v_and_b32_e32 v17, 0xffff0000, v12
	v_lshlrev_b32_e32 v12, 16, v13
	v_and_b32_e32 v13, 0xffff0000, v13
	s_cmpk_gt_u32 s91, 0xff
	s_waitcnt vmcnt(2)
	v_lshlrev_b32_e32 v32, 16, v0
	v_and_b32_e32 v33, 0xffff0000, v0
	v_pk_mul_f32 v[16:17], v[16:17], v[32:33]
	v_add_u32_e32 v32, 24, v116
	v_ashrrev_i32_e32 v33, 31, v32
	v_lshlrev_b64 v[34:35], 11, v[32:33]
	v_cvt_pk_bf16_f32 v0, v16, v17
	v_lshl_add_u64 v[16:17], v[18:19], 0, v[34:35]
	global_load_dwordx4 v[16:19], v[16:17], off
	v_lshlrev_b32_e32 v36, 16, v1
	v_and_b32_e32 v37, 0xffff0000, v1
	v_pk_mul_f32 v[12:13], v[12:13], v[36:37]
	v_lshlrev_b32_e32 v36, 16, v2
	v_cvt_pk_bf16_f32 v1, v12, v13
	v_lshlrev_b32_e32 v12, 16, v14
	v_and_b32_e32 v13, 0xffff0000, v14
	v_and_b32_e32 v37, 0xffff0000, v2
	v_pk_mul_f32 v[12:13], v[12:13], v[36:37]
	v_lshlrev_b32_e32 v38, 16, v3
	v_and_b32_e32 v39, 0xffff0000, v3
	v_lshl_add_u32 v3, v22, 7, v27
	v_cvt_pk_bf16_f32 v2, v12, v13
	v_lshlrev_b32_e32 v36, 16, v15
	v_and_b32_e32 v37, 0xffff0000, v15
	ds_read_b128 v[12:15], v3
	v_pk_mul_f32 v[22:23], v[36:37], v[38:39]
	s_nop 0
	v_cvt_pk_bf16_f32 v3, v22, v23
	global_store_dwordx4 v[20:21], v[0:3], off sc1
	s_waitcnt lgkmcnt(0)
	s_nop 0
	v_lshlrev_b32_e32 v0, 16, v12
	v_and_b32_e32 v1, 0xffff0000, v12
	s_waitcnt vmcnt(3)
	v_lshlrev_b32_e32 v2, 16, v4
	v_and_b32_e32 v3, 0xffff0000, v4
	v_pk_mul_f32 v[0:1], v[0:1], v[2:3]
	v_lshlrev_b32_e32 v2, 16, v13
	v_and_b32_e32 v3, 0xffff0000, v13
	v_lshlrev_b32_e32 v4, 16, v5
	v_and_b32_e32 v5, 0xffff0000, v5
	v_pk_mul_f32 v[2:3], v[2:3], v[4:5]
	v_cvt_pk_bf16_f32 v0, v0, v1
	v_cvt_pk_bf16_f32 v1, v2, v3
	v_lshlrev_b32_e32 v2, 16, v14
	v_and_b32_e32 v3, 0xffff0000, v14
	v_lshlrev_b32_e32 v4, 16, v6
	v_and_b32_e32 v5, 0xffff0000, v6
	v_pk_mul_f32 v[2:3], v[2:3], v[4:5]
	v_lshlrev_b32_e32 v12, 16, v15
	v_cvt_pk_bf16_f32 v2, v2, v3
	v_lshl_add_u32 v3, v26, 7, v27
	v_and_b32_e32 v13, 0xffff0000, v15
	v_lshlrev_b32_e32 v14, 16, v7
	v_and_b32_e32 v15, 0xffff0000, v7
	ds_read_b128 v[4:7], v3
	v_pk_mul_f32 v[12:13], v[12:13], v[14:15]
	s_nop 0
	v_cvt_pk_bf16_f32 v3, v12, v13
	v_lshl_add_u64 v[12:13], v[30:31], 0, v[24:25]
	global_store_dwordx4 v[12:13], v[0:3], off sc1
	s_waitcnt lgkmcnt(0)
	s_nop 0
	v_lshlrev_b32_e32 v0, 16, v4
	v_and_b32_e32 v1, 0xffff0000, v4
	s_waitcnt vmcnt(3)
	v_lshlrev_b32_e32 v2, 16, v8
	v_and_b32_e32 v3, 0xffff0000, v8
	v_pk_mul_f32 v[0:1], v[0:1], v[2:3]
	v_lshlrev_b32_e32 v2, 16, v5
	v_and_b32_e32 v3, 0xffff0000, v5
	v_lshlrev_b32_e32 v4, 16, v9
	v_and_b32_e32 v5, 0xffff0000, v9
	v_pk_mul_f32 v[2:3], v[2:3], v[4:5]
	v_cvt_pk_bf16_f32 v0, v0, v1
	v_cvt_pk_bf16_f32 v1, v2, v3
	v_lshlrev_b32_e32 v2, 16, v6
	v_and_b32_e32 v3, 0xffff0000, v6
	v_lshlrev_b32_e32 v4, 16, v10
	v_and_b32_e32 v5, 0xffff0000, v10
	v_pk_mul_f32 v[2:3], v[2:3], v[4:5]
	v_lshlrev_b32_e32 v8, 16, v7
	v_cvt_pk_bf16_f32 v2, v2, v3
	v_lshl_add_u32 v3, v32, 7, v27
	v_and_b32_e32 v9, 0xffff0000, v7
	ds_read_b128 v[4:7], v3
	v_lshlrev_b32_e32 v10, 16, v11
	v_and_b32_e32 v11, 0xffff0000, v11
	v_pk_mul_f32 v[8:9], v[8:9], v[10:11]
	s_nop 0
	v_cvt_pk_bf16_f32 v3, v8, v9
	v_lshl_add_u64 v[8:9], v[30:31], 0, v[28:29]
	global_store_dwordx4 v[8:9], v[0:3], off sc1
	s_waitcnt lgkmcnt(0)
	s_nop 0
	v_lshlrev_b32_e32 v0, 16, v4
	v_and_b32_e32 v1, 0xffff0000, v4
	s_waitcnt vmcnt(3)
	v_lshlrev_b32_e32 v2, 16, v16
	v_and_b32_e32 v3, 0xffff0000, v16
	v_pk_mul_f32 v[0:1], v[0:1], v[2:3]
	v_lshlrev_b32_e32 v2, 16, v5
	v_and_b32_e32 v3, 0xffff0000, v5
	v_lshlrev_b32_e32 v4, 16, v17
	v_and_b32_e32 v5, 0xffff0000, v17
	v_pk_mul_f32 v[2:3], v[2:3], v[4:5]
	v_cvt_pk_bf16_f32 v0, v0, v1
	v_cvt_pk_bf16_f32 v1, v2, v3
	v_lshlrev_b32_e32 v2, 16, v6
	v_and_b32_e32 v3, 0xffff0000, v6
	v_lshlrev_b32_e32 v4, 16, v18
	v_and_b32_e32 v5, 0xffff0000, v18
	v_pk_mul_f32 v[2:3], v[2:3], v[4:5]
	v_lshlrev_b32_e32 v4, 16, v7
	v_and_b32_e32 v5, 0xffff0000, v7
	v_lshlrev_b32_e32 v6, 16, v19
	v_and_b32_e32 v7, 0xffff0000, v19
	v_pk_mul_f32 v[4:5], v[4:5], v[6:7]
	v_cvt_pk_bf16_f32 v2, v2, v3
	v_cvt_pk_bf16_f32 v3, v4, v5
	v_lshl_add_u64 v[4:5], v[30:31], 0, v[34:35]
	global_store_dwordx4 v[4:5], v[0:3], off sc1
	s_waitcnt lgkmcnt(0)
	s_barrier
	s_cbranch_scc0 .LBB0_1017
	s_add_i32 s0, s90, -4
	s_mul_i32 s0, s0, s68
	s_add_i32 s0, s0, s94
	s_addk_i32 s0, 0x800
	s_ashr_i32 s1, s0, 31
	s_lshr_b32 s1, s1, 25
	s_add_i32 s1, s0, s1
	s_ashr_i32 s2, s1, 7
	s_and_b32 s1, s1, 0xffffff80
	s_sub_i32 s18, s0, s1
	s_mul_hi_i32 s0, s0, 0x2aaaaaab
	s_lshr_b32 s1, s0, 31
	s_ashr_i32 s0, s0, 8
	s_add_i32 s26, s0, s1
	s_mul_hi_i32 s0, s2, 0x2aaaaaab
	s_lshr_b32 s1, s0, 31
	s_lshr_b32 s0, s0, 1
	s_add_i32 s0, s0, s1
	s_mul_i32 s0, s0, 12
	s_ashr_i32 s27, s26, 31
	s_ashr_i32 s19, s18, 31
	s_lshl_b32 s4, s18, 6
	s_sub_i32 s24, s2, s0
	s_lshl_b64 s[0:1], s[26:27], 13
	s_lshl_b64 s[2:3], s[18:19], 6
	s_sub_i32 s19, 2, s4
	s_add_u32 s0, s0, s2
	s_addc_u32 s1, s1, s3
	s_add_u32 s34, s0, -3
	s_addc_u32 s35, s1, -1
	s_lshl_b32 s22, s24, 6
	s_ashr_i32 s23, s22, 31
	s_lshl_b64 s[0:1], s[22:23], 1
	s_add_u32 s0, s38, s0
	s_addc_u32 s1, s39, s1
	s_movk_i32 s4, 0x43
	v_lshl_add_u64 v[0:1], s[0:1], 0, v[124:125]
	v_cmp_gt_i32_e64 s[0:1], s4, v116
	v_cmp_lt_i32_e32 vcc, s19, v116
	s_and_b64 s[6:7], s[0:1], vcc
	v_mov_b32_e32 v65, v125
	v_mov_b32_e32 v66, v125
	v_mov_b32_e32 v67, v125
	s_and_saveexec_b64 s[2:3], s[6:7]
	s_cbranch_execz .LBB0_984
	v_lshl_add_u64 v[2:3], s[34:35], 0, v[116:117]
	s_movk_i32 s5, 0x600
	v_mad_u64_u32 v[4:5], s[6:7], v2, s5, v[0:1]
	v_mad_i32_i24 v5, v3, s5, v5
	global_load_dwordx4 v[64:67], v[4:5], off
	s_waitcnt vmcnt(0)
	v_mov_b32_e32 v125, v64
